# residual-GEMM epilogue stores made write-through (sc1) so the grid-barrier release fence has less dirty L2 data to flush; on top of the combined version
# baseline (speedup 1.0000x reference)
; #define GAS __attribute__((address_space(1)))
;     __device__ __forceinline__ void operator()(const f32x4 (&acc)[2][2][4][2], const Unit& u, int wr, int wc, int fr, int fq) const {
;     ...
;         for (int bj = 0; bj < 2; ++bj) {
;             f32x4 hv[2][2][4];
; #pragma unroll
;             for (int n = 0; n < 2; ++n)
; #pragma unroll
;                 for (int ai = 0; ai < 2; ++ai)
; #pragma unroll
;                     for (int m = 0; m < 4; ++m) hv[n][ai][m] = *(const GAS f32x4*)(row0 + (size_t)(ai * HALF + m * 16) * 1024 + bj * HALF + n * 16);
;             asm volatile("" ::: "memory");
; #pragma unroll
;             for (int n = 0; n < 2; ++n) { const f32x4 gv = *(const GAS f32x4*)(gp + bj * HALF + n * 16) * mul;
; #pragma unroll
;                 for (int ai = 0; ai < 2; ++ai)
; #pragma unroll
;                     for (int m = 0; m < 4; ++m) *(GAS f32x4*)(row0 + (size_t)(ai * HALF + m * 16) * 1024 + bj * HALF + n * 16) = hv[n][ai][m] + gv * acc[ai][bj][m][n]; }
.LBB0_822:
	v_add_co_u32_e32 v150, vcc, 0x10000, v146
	s_nop 1
	v_addc_co_u32_e32 v151, vcc, 0, v147, vcc
	v_add_co_u32_e32 v152, vcc, 0x20000, v146
	s_nop 1
	v_addc_co_u32_e32 v153, vcc, 0, v147, vcc
	v_add_co_u32_e32 v154, vcc, 0x30000, v146
	s_nop 1
	v_addc_co_u32_e32 v155, vcc, 0, v147, vcc
	v_add_co_u32_e32 v156, vcc, 0x80000, v146
	s_nop 1
	v_addc_co_u32_e32 v157, vcc, 0, v147, vcc
	v_add_co_u32_e32 v158, vcc, 0x90000, v146
	s_nop 1
	v_addc_co_u32_e32 v159, vcc, 0, v147, vcc
	v_add_co_u32_e32 v160, vcc, s21, v146
	s_nop 1
	v_addc_co_u32_e32 v161, vcc, 0, v147, vcc
	v_add_co_u32_e32 v162, vcc, 0xb0000, v146
	s_nop 1
	v_addc_co_u32_e32 v163, vcc, 0, v147, vcc
	global_load_dwordx4 v[184:187], v[146:147], off
	global_load_dwordx4 v[188:191], v[146:147], off offset:64
	global_load_dwordx4 v[192:195], v[150:151], off
	global_load_dwordx4 v[196:199], v[150:151], off offset:64
	global_load_dwordx4 v[200:203], v[152:153], off
	global_load_dwordx4 v[204:207], v[152:153], off offset:64
	global_load_dwordx4 v[208:211], v[154:155], off
	global_load_dwordx4 v[212:215], v[154:155], off offset:64
	global_load_dwordx4 v[216:219], v[156:157], off
	global_load_dwordx4 v[220:223], v[156:157], off offset:64
	global_load_dwordx4 v[224:227], v[158:159], off
	global_load_dwordx4 v[228:231], v[158:159], off offset:64
	global_load_dwordx4 v[232:235], v[160:161], off
	global_load_dwordx4 v[236:239], v[160:161], off offset:64
	global_load_dwordx4 v[240:243], v[162:163], off
	global_load_dwordx4 v[244:247], v[162:163], off offset:64
	global_load_dwordx4 v[180:183], v[148:149], off
	s_waitcnt vmcnt(0)
	v_pk_fma_f32 v[186:187], v[126:127], v[182:183], v[186:187]
	v_pk_fma_f32 v[184:185], v[124:125], v[180:181], v[184:185]
	v_pk_fma_f32 v[194:195], v[122:123], v[182:183], v[194:195]
	v_pk_fma_f32 v[192:193], v[120:121], v[180:181], v[192:193]
	v_pk_fma_f32 v[202:203], v[118:119], v[182:183], v[202:203]
	v_pk_fma_f32 v[200:201], v[116:117], v[180:181], v[200:201]
	v_pk_fma_f32 v[210:211], v[114:115], v[182:183], v[210:211]
	v_pk_fma_f32 v[208:209], v[112:113], v[180:181], v[208:209]
	v_pk_fma_f32 v[218:219], v[110:111], v[182:183], v[218:219]
	v_pk_fma_f32 v[216:217], v[108:109], v[180:181], v[216:217]
	v_pk_fma_f32 v[226:227], v[106:107], v[182:183], v[226:227]
	v_pk_fma_f32 v[224:225], v[104:105], v[180:181], v[224:225]
	v_pk_fma_f32 v[234:235], v[102:103], v[182:183], v[234:235]
	v_pk_fma_f32 v[232:233], v[100:101], v[180:181], v[232:233]
	v_pk_fma_f32 v[182:183], v[98:99], v[182:183], v[242:243]
	v_pk_fma_f32 v[180:181], v[96:97], v[180:181], v[240:241]
	global_store_dwordx4 v[146:147], v[184:187], off sc1
	global_store_dwordx4 v[150:151], v[192:195], off sc1
	global_store_dwordx4 v[152:153], v[200:203], off sc1
	global_store_dwordx4 v[154:155], v[208:211], off sc1
	global_store_dwordx4 v[156:157], v[216:219], off sc1
	global_store_dwordx4 v[158:159], v[224:227], off sc1
	global_store_dwordx4 v[160:161], v[232:235], off sc1
	global_store_dwordx4 v[162:163], v[180:183], off sc1
	global_load_dwordx4 v[180:183], v[148:149], off offset:64
	s_waitcnt vmcnt(0)
; #define GAS __attribute__((address_space(1)))
;     __device__ __forceinline__ void operator()(const f32x4 (&acc)[2][2][4][2], const Unit& u, int wr, int wc, int fr, int fq) const {
;     ...
;         for (int bj = 0; bj < 2; ++bj) {
;             f32x4 hv[2][2][4];
; #pragma unroll
;             for (int n = 0; n < 2; ++n)
; #pragma unroll
;                 for (int ai = 0; ai < 2; ++ai)
; #pragma unroll
;                     for (int m = 0; m < 4; ++m) hv[n][ai][m] = *(const GAS f32x4*)(row0 + (size_t)(ai * HALF + m * 16) * 1024 + bj * HALF + n * 16);
;             asm volatile("" ::: "memory");
; #pragma unroll
;             for (int n = 0; n < 2; ++n) { const f32x4 gv = *(const GAS f32x4*)(gp + bj * HALF + n * 16) * mul;
; #pragma unroll
;                 for (int ai = 0; ai < 2; ++ai)
; #pragma unroll
;                     for (int m = 0; m < 4; ++m) *(GAS f32x4*)(row0 + (size_t)(ai * HALF + m * 16) * 1024 + bj * HALF + n * 16) = hv[n][ai][m] + gv * acc[ai][bj][m][n]; }
;             asm volatile("" ::: "memory"); }
	v_pk_fma_f32 v[186:187], v[94:95], v[182:183], v[190:191]
	v_pk_fma_f32 v[184:185], v[92:93], v[180:181], v[188:189]
	v_pk_fma_f32 v[190:191], v[90:91], v[182:183], v[198:199]
	v_pk_fma_f32 v[188:189], v[88:89], v[180:181], v[196:197]
	v_pk_fma_f32 v[194:195], v[86:87], v[182:183], v[206:207]
	v_pk_fma_f32 v[192:193], v[84:85], v[180:181], v[204:205]
	v_pk_fma_f32 v[198:199], v[82:83], v[182:183], v[214:215]
	v_pk_fma_f32 v[196:197], v[80:81], v[180:181], v[212:213]
	v_pk_fma_f32 v[202:203], v[78:79], v[182:183], v[222:223]
	v_pk_fma_f32 v[200:201], v[76:77], v[180:181], v[220:221]
	v_pk_fma_f32 v[206:207], v[74:75], v[182:183], v[230:231]
	v_pk_fma_f32 v[204:205], v[72:73], v[180:181], v[228:229]
	v_pk_fma_f32 v[210:211], v[70:71], v[182:183], v[238:239]
	v_pk_fma_f32 v[208:209], v[68:69], v[180:181], v[236:237]
	v_pk_fma_f32 v[182:183], v[62:63], v[182:183], v[246:247]
	v_pk_fma_f32 v[180:181], v[60:61], v[180:181], v[244:245]
	global_store_dwordx4 v[146:147], v[184:187], off offset:64 sc1
	global_store_dwordx4 v[150:151], v[188:191], off offset:64 sc1
	global_store_dwordx4 v[152:153], v[192:195], off offset:64 sc1
	global_store_dwordx4 v[154:155], v[196:199], off offset:64 sc1
	global_store_dwordx4 v[156:157], v[200:203], off offset:64 sc1
	global_store_dwordx4 v[158:159], v[204:207], off offset:64 sc1
	global_store_dwordx4 v[160:161], v[208:211], off offset:64 sc1
	global_store_dwordx4 v[162:163], v[180:183], off offset:64 sc1
	global_load_dwordx4 v[180:183], v[146:147], off offset:512
	global_load_dwordx4 v[184:187], v[146:147], off offset:576
	global_load_dwordx4 v[188:191], v[150:151], off offset:512
	global_load_dwordx4 v[192:195], v[150:151], off offset:576
	global_load_dwordx4 v[196:199], v[152:153], off offset:512
	global_load_dwordx4 v[200:203], v[152:153], off offset:576
	global_load_dwordx4 v[204:207], v[154:155], off offset:512
	global_load_dwordx4 v[208:211], v[154:155], off offset:576
	global_load_dwordx4 v[212:215], v[156:157], off offset:512
	global_load_dwordx4 v[216:219], v[156:157], off offset:576
	global_load_dwordx4 v[220:223], v[158:159], off offset:512
	global_load_dwordx4 v[224:227], v[158:159], off offset:576
	global_load_dwordx4 v[228:231], v[160:161], off offset:512
	global_load_dwordx4 v[232:235], v[160:161], off offset:576
	global_load_dwordx4 v[236:239], v[162:163], off offset:512
	global_load_dwordx4 v[240:243], v[162:163], off offset:576
	global_load_dwordx4 v[244:247], v[148:149], off offset:512
	s_waitcnt vmcnt(0)
	v_pk_fma_f32 v[182:183], v[66:67], v[246:247], v[182:183]
	v_pk_fma_f32 v[180:181], v[64:65], v[244:245], v[180:181]
	v_pk_fma_f32 v[190:191], v[58:59], v[246:247], v[190:191]
	v_pk_fma_f32 v[188:189], v[56:57], v[244:245], v[188:189]
	v_pk_fma_f32 v[198:199], v[54:55], v[246:247], v[198:199]
	v_pk_fma_f32 v[196:197], v[52:53], v[244:245], v[196:197]
	v_pk_fma_f32 v[206:207], v[50:51], v[246:247], v[206:207]
	v_pk_fma_f32 v[204:205], v[48:49], v[244:245], v[204:205]
	v_pk_fma_f32 v[214:215], v[46:47], v[246:247], v[214:215]
	v_pk_fma_f32 v[212:213], v[44:45], v[244:245], v[212:213]
	v_pk_fma_f32 v[222:223], v[38:39], v[246:247], v[222:223]
	v_pk_fma_f32 v[220:221], v[36:37], v[244:245], v[220:221]
	v_pk_fma_f32 v[230:231], v[30:31], v[246:247], v[230:231]
	v_pk_fma_f32 v[228:229], v[28:29], v[244:245], v[228:229]
	v_pk_fma_f32 v[238:239], v[22:23], v[246:247], v[238:239]
	v_pk_fma_f32 v[236:237], v[20:21], v[244:245], v[236:237]
	global_store_dwordx4 v[146:147], v[180:183], off offset:512 sc1
	global_store_dwordx4 v[150:151], v[188:191], off offset:512 sc1
	global_store_dwordx4 v[152:153], v[196:199], off offset:512 sc1
	global_store_dwordx4 v[154:155], v[204:207], off offset:512 sc1
	global_store_dwordx4 v[156:157], v[212:215], off offset:512 sc1
	global_store_dwordx4 v[158:159], v[220:223], off offset:512 sc1
	global_store_dwordx4 v[160:161], v[228:231], off offset:512 sc1
	global_store_dwordx4 v[162:163], v[236:239], off offset:512 sc1
	global_load_dwordx4 v[180:183], v[148:149], off offset:576
	s_waitcnt vmcnt(0)
	v_pk_fma_f32 v[186:187], v[42:43], v[182:183], v[186:187]
	v_pk_fma_f32 v[184:185], v[40:41], v[180:181], v[184:185]
	v_pk_fma_f32 v[190:191], v[34:35], v[182:183], v[194:195]
	v_pk_fma_f32 v[188:189], v[32:33], v[180:181], v[192:193]
	v_pk_fma_f32 v[194:195], v[26:27], v[182:183], v[202:203]
	v_pk_fma_f32 v[192:193], v[24:25], v[180:181], v[200:201]
	v_pk_fma_f32 v[198:199], v[18:19], v[182:183], v[210:211]
	v_pk_fma_f32 v[196:197], v[16:17], v[180:181], v[208:209]
	v_pk_fma_f32 v[202:203], v[14:15], v[182:183], v[218:219]
	v_pk_fma_f32 v[200:201], v[12:13], v[180:181], v[216:217]
	v_pk_fma_f32 v[206:207], v[10:11], v[182:183], v[226:227]
	v_pk_fma_f32 v[204:205], v[8:9], v[180:181], v[224:225]
	v_pk_fma_f32 v[210:211], v[6:7], v[182:183], v[234:235]
	v_pk_fma_f32 v[208:209], v[4:5], v[180:181], v[232:233]
	v_pk_fma_f32 v[182:183], v[2:3], v[182:183], v[242:243]
	v_pk_fma_f32 v[180:181], v[0:1], v[180:181], v[240:241]
	global_store_dwordx4 v[146:147], v[184:187], off offset:576 sc1
	global_store_dwordx4 v[150:151], v[188:191], off offset:576 sc1
	global_store_dwordx4 v[152:153], v[192:195], off offset:576 sc1
	global_store_dwordx4 v[154:155], v[196:199], off offset:576 sc1
	global_store_dwordx4 v[156:157], v[200:203], off offset:576 sc1
	global_store_dwordx4 v[158:159], v[204:207], off offset:576 sc1
	global_store_dwordx4 v[160:161], v[208:211], off offset:576 sc1
	global_store_dwordx4 v[162:163], v[180:183], off offset:576 sc1
	s_cbranch_execnz .LBB0_821

; #define GAS __attribute__((address_space(1)))
;     __device__ __forceinline__ void operator()(const f32x4 (&acc)[2][2][4][2], const Unit& u, int wr, int wc, int fr, int fq) const {
;     ...
;         for (int bj = 0; bj < 2; ++bj) {
;             f32x4 hv[2][2][4];
; #pragma unroll
;             for (int n = 0; n < 2; ++n)
; #pragma unroll
;                 for (int ai = 0; ai < 2; ++ai)
; #pragma unroll
;                     for (int m = 0; m < 4; ++m) hv[n][ai][m] = *(const GAS f32x4*)(row0 + (size_t)(ai * HALF + m * 16) * 1024 + bj * HALF + n * 16);
;             asm volatile("" ::: "memory");
; #pragma unroll
;             for (int n = 0; n < 2; ++n) { const f32x4 gv = *(const GAS f32x4*)(gp + bj * HALF + n * 16) * mul;
; #pragma unroll
;                 for (int ai = 0; ai < 2; ++ai)
; #pragma unroll
;                     for (int m = 0; m < 4; ++m) *(GAS f32x4*)(row0 + (size_t)(ai * HALF + m * 16) * 1024 + bj * HALF + n * 16) = hv[n][ai][m] + gv * acc[ai][bj][m][n]; }
.LBB0_1083:
	v_add_co_u32_e32 v150, vcc, 0x10000, v146
	s_nop 1
	v_addc_co_u32_e32 v151, vcc, 0, v147, vcc
	v_add_co_u32_e32 v152, vcc, 0x20000, v146
	s_nop 1
	v_addc_co_u32_e32 v153, vcc, 0, v147, vcc
	v_add_co_u32_e32 v154, vcc, 0x30000, v146
	s_nop 1
	v_addc_co_u32_e32 v155, vcc, 0, v147, vcc
	v_add_co_u32_e32 v156, vcc, 0x80000, v146
	s_nop 1
	v_addc_co_u32_e32 v157, vcc, 0, v147, vcc
	v_add_co_u32_e32 v158, vcc, 0x90000, v146
	s_nop 1
	v_addc_co_u32_e32 v159, vcc, 0, v147, vcc
	v_add_co_u32_e32 v160, vcc, s19, v146
	s_nop 1
	v_addc_co_u32_e32 v161, vcc, 0, v147, vcc
	v_add_co_u32_e32 v162, vcc, 0xb0000, v146
	s_nop 1
	v_addc_co_u32_e32 v163, vcc, 0, v147, vcc
	global_load_dwordx4 v[180:183], v[146:147], off
	global_load_dwordx4 v[184:187], v[146:147], off offset:64
	global_load_dwordx4 v[188:191], v[150:151], off
	global_load_dwordx4 v[192:195], v[150:151], off offset:64
	global_load_dwordx4 v[196:199], v[152:153], off
	global_load_dwordx4 v[200:203], v[152:153], off offset:64
	global_load_dwordx4 v[204:207], v[154:155], off
	global_load_dwordx4 v[208:211], v[154:155], off offset:64
	global_load_dwordx4 v[212:215], v[156:157], off
	global_load_dwordx4 v[216:219], v[156:157], off offset:64
	global_load_dwordx4 v[220:223], v[158:159], off
	global_load_dwordx4 v[224:227], v[158:159], off offset:64
	global_load_dwordx4 v[228:231], v[160:161], off
	global_load_dwordx4 v[232:235], v[160:161], off offset:64
	global_load_dwordx4 v[236:239], v[162:163], off
	global_load_dwordx4 v[240:243], v[162:163], off offset:64
	global_load_dwordx4 v[244:247], v[148:149], off
	s_waitcnt vmcnt(0)
	v_pk_mul_f32 v[246:247], v[246:247], 0.5 op_sel_hi:[1,0]
	v_pk_mul_f32 v[244:245], v[244:245], 0.5 op_sel_hi:[1,0]
	v_pk_fma_f32 v[182:183], v[126:127], v[246:247], v[182:183]
	v_pk_fma_f32 v[180:181], v[124:125], v[244:245], v[180:181]
	v_pk_fma_f32 v[190:191], v[122:123], v[246:247], v[190:191]
	v_pk_fma_f32 v[188:189], v[120:121], v[244:245], v[188:189]
	v_pk_fma_f32 v[198:199], v[118:119], v[246:247], v[198:199]
	v_pk_fma_f32 v[196:197], v[116:117], v[244:245], v[196:197]
	v_pk_fma_f32 v[206:207], v[114:115], v[246:247], v[206:207]
	v_pk_fma_f32 v[204:205], v[112:113], v[244:245], v[204:205]
	v_pk_fma_f32 v[214:215], v[110:111], v[246:247], v[214:215]
	v_pk_fma_f32 v[212:213], v[108:109], v[244:245], v[212:213]
	v_pk_fma_f32 v[222:223], v[106:107], v[246:247], v[222:223]
	v_pk_fma_f32 v[220:221], v[104:105], v[244:245], v[220:221]
	v_pk_fma_f32 v[230:231], v[102:103], v[246:247], v[230:231]
	v_pk_fma_f32 v[228:229], v[100:101], v[244:245], v[228:229]
	v_pk_fma_f32 v[238:239], v[98:99], v[246:247], v[238:239]
	v_pk_fma_f32 v[236:237], v[96:97], v[244:245], v[236:237]
	global_store_dwordx4 v[146:147], v[180:183], off sc1
	global_store_dwordx4 v[150:151], v[188:191], off sc1
	global_store_dwordx4 v[152:153], v[196:199], off sc1
	global_store_dwordx4 v[154:155], v[204:207], off sc1
	global_store_dwordx4 v[156:157], v[212:215], off sc1
	global_store_dwordx4 v[158:159], v[220:223], off sc1
	global_store_dwordx4 v[160:161], v[228:231], off sc1
	global_store_dwordx4 v[162:163], v[236:239], off sc1
	global_load_dwordx4 v[180:183], v[148:149], off offset:64
	s_waitcnt vmcnt(0)
	v_pk_mul_f32 v[212:213], v[182:183], 0.5 op_sel_hi:[1,0]
	v_pk_mul_f32 v[214:215], v[180:181], 0.5 op_sel_hi:[1,0]
	v_pk_fma_f32 v[182:183], v[94:95], v[212:213], v[186:187]
	v_pk_fma_f32 v[180:181], v[92:93], v[214:215], v[184:185]
	v_pk_fma_f32 v[186:187], v[90:91], v[212:213], v[194:195]
	v_pk_fma_f32 v[184:185], v[88:89], v[214:215], v[192:193]
	v_pk_fma_f32 v[190:191], v[86:87], v[212:213], v[202:203]
	v_pk_fma_f32 v[188:189], v[84:85], v[214:215], v[200:201]
	v_pk_fma_f32 v[194:195], v[82:83], v[212:213], v[210:211]
	v_pk_fma_f32 v[192:193], v[80:81], v[214:215], v[208:209]
	v_pk_fma_f32 v[198:199], v[78:79], v[212:213], v[218:219]
	v_pk_fma_f32 v[196:197], v[76:77], v[214:215], v[216:217]
	v_pk_fma_f32 v[202:203], v[74:75], v[212:213], v[226:227]
	v_pk_fma_f32 v[200:201], v[72:73], v[214:215], v[224:225]
	v_pk_fma_f32 v[206:207], v[70:71], v[212:213], v[234:235]
	v_pk_fma_f32 v[204:205], v[68:69], v[214:215], v[232:233]
	v_pk_fma_f32 v[210:211], v[66:67], v[212:213], v[242:243]
	v_pk_fma_f32 v[208:209], v[64:65], v[214:215], v[240:241]
	global_store_dwordx4 v[146:147], v[180:183], off offset:64 sc1
	global_store_dwordx4 v[150:151], v[184:187], off offset:64 sc1
	global_store_dwordx4 v[152:153], v[188:191], off offset:64 sc1
	global_store_dwordx4 v[154:155], v[192:195], off offset:64 sc1
	global_store_dwordx4 v[156:157], v[196:199], off offset:64 sc1
	global_store_dwordx4 v[158:159], v[200:203], off offset:64 sc1
	global_store_dwordx4 v[160:161], v[204:207], off offset:64 sc1
	global_store_dwordx4 v[162:163], v[208:211], off offset:64 sc1
	global_load_dwordx4 v[180:183], v[146:147], off offset:512
	global_load_dwordx4 v[184:187], v[146:147], off offset:576
	global_load_dwordx4 v[188:191], v[150:151], off offset:512
	global_load_dwordx4 v[192:195], v[150:151], off offset:576
	global_load_dwordx4 v[196:199], v[152:153], off offset:512
	global_load_dwordx4 v[200:203], v[152:153], off offset:576
	global_load_dwordx4 v[204:207], v[154:155], off offset:512
	global_load_dwordx4 v[208:211], v[154:155], off offset:576
	global_load_dwordx4 v[212:215], v[156:157], off offset:512
	global_load_dwordx4 v[216:219], v[156:157], off offset:576
	global_load_dwordx4 v[220:223], v[158:159], off offset:512
	global_load_dwordx4 v[224:227], v[158:159], off offset:576
	global_load_dwordx4 v[228:231], v[160:161], off offset:512
	global_load_dwordx4 v[232:235], v[160:161], off offset:576
	global_load_dwordx4 v[236:239], v[162:163], off offset:512
	global_load_dwordx4 v[240:243], v[162:163], off offset:576
	global_load_dwordx4 v[244:247], v[148:149], off offset:512
	s_waitcnt vmcnt(0)
; #define GAS __attribute__((address_space(1)))
;     __device__ __forceinline__ void operator()(const f32x4 (&acc)[2][2][4][2], const Unit& u, int wr, int wc, int fr, int fq) const {
;     ...
;         for (int bj = 0; bj < 2; ++bj) {
;             f32x4 hv[2][2][4];
; #pragma unroll
;             for (int n = 0; n < 2; ++n)
; #pragma unroll
;                 for (int ai = 0; ai < 2; ++ai)
; #pragma unroll
;                     for (int m = 0; m < 4; ++m) hv[n][ai][m] = *(const GAS f32x4*)(row0 + (size_t)(ai * HALF + m * 16) * 1024 + bj * HALF + n * 16);
;             asm volatile("" ::: "memory");
; #pragma unroll
;             for (int n = 0; n < 2; ++n) { const f32x4 gv = *(const GAS f32x4*)(gp + bj * HALF + n * 16) * mul;
; #pragma unroll
;                 for (int ai = 0; ai < 2; ++ai)
; #pragma unroll
;                     for (int m = 0; m < 4; ++m) *(GAS f32x4*)(row0 + (size_t)(ai * HALF + m * 16) * 1024 + bj * HALF + n * 16) = hv[n][ai][m] + gv * acc[ai][bj][m][n]; }
;             asm volatile("" ::: "memory"); }
	v_pk_mul_f32 v[246:247], v[246:247], 0.5 op_sel_hi:[1,0]
	v_pk_mul_f32 v[244:245], v[244:245], 0.5 op_sel_hi:[1,0]
	v_pk_fma_f32 v[182:183], v[62:63], v[246:247], v[182:183]
	v_pk_fma_f32 v[180:181], v[60:61], v[244:245], v[180:181]
	v_pk_fma_f32 v[190:191], v[58:59], v[246:247], v[190:191]
	v_pk_fma_f32 v[188:189], v[56:57], v[244:245], v[188:189]
	v_pk_fma_f32 v[198:199], v[54:55], v[246:247], v[198:199]
	v_pk_fma_f32 v[196:197], v[52:53], v[244:245], v[196:197]
	v_pk_fma_f32 v[206:207], v[50:51], v[246:247], v[206:207]
	v_pk_fma_f32 v[204:205], v[48:49], v[244:245], v[204:205]
	v_pk_fma_f32 v[214:215], v[46:47], v[246:247], v[214:215]
	v_pk_fma_f32 v[212:213], v[44:45], v[244:245], v[212:213]
	v_pk_fma_f32 v[222:223], v[42:43], v[246:247], v[222:223]
	v_pk_fma_f32 v[220:221], v[40:41], v[244:245], v[220:221]
	v_pk_fma_f32 v[230:231], v[38:39], v[246:247], v[230:231]
	v_pk_fma_f32 v[228:229], v[36:37], v[244:245], v[228:229]
	v_pk_fma_f32 v[238:239], v[34:35], v[246:247], v[238:239]
	v_pk_fma_f32 v[236:237], v[32:33], v[244:245], v[236:237]
	global_store_dwordx4 v[146:147], v[180:183], off offset:512 sc1
	global_store_dwordx4 v[150:151], v[188:191], off offset:512 sc1
	global_store_dwordx4 v[152:153], v[196:199], off offset:512 sc1
	global_store_dwordx4 v[154:155], v[204:207], off offset:512 sc1
	global_store_dwordx4 v[156:157], v[212:215], off offset:512 sc1
	global_store_dwordx4 v[158:159], v[220:223], off offset:512 sc1
	global_store_dwordx4 v[160:161], v[228:231], off offset:512 sc1
	global_store_dwordx4 v[162:163], v[236:239], off offset:512 sc1
	global_load_dwordx4 v[180:183], v[148:149], off offset:576
	s_waitcnt vmcnt(0)
	v_pk_mul_f32 v[212:213], v[182:183], 0.5 op_sel_hi:[1,0]
	v_pk_mul_f32 v[214:215], v[180:181], 0.5 op_sel_hi:[1,0]
	v_pk_fma_f32 v[182:183], v[30:31], v[212:213], v[186:187]
	v_pk_fma_f32 v[180:181], v[28:29], v[214:215], v[184:185]
	v_pk_fma_f32 v[186:187], v[26:27], v[212:213], v[194:195]
	v_pk_fma_f32 v[184:185], v[24:25], v[214:215], v[192:193]
	v_pk_fma_f32 v[190:191], v[22:23], v[212:213], v[202:203]
	v_pk_fma_f32 v[188:189], v[20:21], v[214:215], v[200:201]
	v_pk_fma_f32 v[194:195], v[18:19], v[212:213], v[210:211]
	v_pk_fma_f32 v[192:193], v[16:17], v[214:215], v[208:209]
	v_pk_fma_f32 v[198:199], v[14:15], v[212:213], v[218:219]
	v_pk_fma_f32 v[196:197], v[12:13], v[214:215], v[216:217]
	v_pk_fma_f32 v[202:203], v[10:11], v[212:213], v[226:227]
	v_pk_fma_f32 v[200:201], v[8:9], v[214:215], v[224:225]
	v_pk_fma_f32 v[206:207], v[6:7], v[212:213], v[234:235]
	v_pk_fma_f32 v[204:205], v[4:5], v[214:215], v[232:233]
	v_pk_fma_f32 v[210:211], v[2:3], v[212:213], v[242:243]
	v_pk_fma_f32 v[208:209], v[0:1], v[214:215], v[240:241]
	global_store_dwordx4 v[146:147], v[180:183], off offset:576 sc1
	global_store_dwordx4 v[150:151], v[184:187], off offset:576 sc1
	global_store_dwordx4 v[152:153], v[188:191], off offset:576 sc1
	global_store_dwordx4 v[154:155], v[192:195], off offset:576 sc1
	global_store_dwordx4 v[156:157], v[196:199], off offset:576 sc1
	global_store_dwordx4 v[158:159], v[200:203], off offset:576 sc1
	global_store_dwordx4 v[160:161], v[204:207], off offset:576 sc1
	global_store_dwordx4 v[162:163], v[208:211], off offset:576 sc1
	s_cbranch_execnz .LBB0_1082
